# v11 + GEMM3 rstd cache + GEMM7 epilogue loads batched + sign-tagged final-norm exchange (all earlier validated pieces combined)
# baseline (speedup 1.0000x reference)
;     __device__ __forceinline__ void operator()(const f32x4 (&acc)[2][2][4][2], const pg8::Unit& u, int wr, int wc, int fr, int fq) const {
;         const int row0 = u.pm * 256 + wr * 64 + fr, col0 = u.pn * 256 + wc * 32 + 8 * fq;
;         const float* rb = (u.pm * 256 < TP) ? res0 : res1;
; #pragma unroll
;         for (int ai = 0; ai < 2; ++ai)
; #pragma unroll
;             for (int mp = 0; mp < 2; ++mp) {
;                 f32x4 x[2][2][2];
; #pragma unroll
;                 for (int mq = 0; mq < 2; ++mq)
; #pragma unroll
;                     for (int bj = 0; bj < 2; ++bj) { const size_t off = (size_t)(row0 + ai * 128 + (2 * mp + mq) * 16) * D + col0 + bj * 128;
;                         if (RB) { const u32x4 r = *(const u32x4*)(resb + off);
;                             x[mq][bj][0] = (f32x4){__builtin_bit_cast(float, r.x << 16), __builtin_bit_cast(float, r.x & 0xffff0000u), __builtin_bit_cast(float, r.y << 16), __builtin_bit_cast(float, r.y & 0xffff0000u)};
;                             x[mq][bj][1] = (f32x4){__builtin_bit_cast(float, r.z << 16), __builtin_bit_cast(float, r.z & 0xffff0000u), __builtin_bit_cast(float, r.w << 16), __builtin_bit_cast(float, r.w & 0xffff0000u)}; }
;                         else { x[mq][bj][0] = *(const f32x4*)(rb + off); x[mq][bj][1] = *(const f32x4*)(rb + off + 4); } }
; #pragma unroll
;                 for (int mq = 0; mq < 2; ++mq) { const int m = 2 * mp + mq, row = row0 + ai * 128 + m * 16; float ss = 0.f;
; #pragma unroll
;                     for (int bj = 0; bj < 2; ++bj) { const size_t off = (size_t)row * D + col0 + bj * 128;
;                         const f32x4 v0 = x[mq][bj][0] + acc[ai][bj][m][0] * scale, v1 = x[mq][bj][1] + acc[ai][bj][m][1] * scale;
;                         if (OF) { *(f32x4*)(out + off) = v0; *(f32x4*)(out + off + 4) = v1; }
;                         if (OB) { u32x4 w; w.x = cvt_pk_bf16(v0[0], v0[1]); w.y = cvt_pk_bf16(v0[2], v0[3]); w.z = cvt_pk_bf16(v1[0], v1[1]); w.w = cvt_pk_bf16(v1[2], v1[3]); *(u32x4*)(outb + off) = w; }
;                         if (WS) ss += ((v0[0] * v0[0] + v0[1] * v0[1]) + (v0[2] * v0[2] + v0[3] * v0[3])) + ((v1[0] * v1[0] + v1[1] * v1[1]) + (v1[2] * v1[2] + v1[3] * v1[3])); }
;                     if (WS) { ss += __shfl_xor(ss, 16); ss += __shfl_xor(ss, 32); if (fq == 0) ssq[(size_t)row * 16 + u.pn * 4 + wc] = ss; } }
.LBB0_772:
	v_lshl_or_b32 v152, s6, 8, v164
	v_lshl_add_u32 v154, s22, 8, v162
	v_ashrrev_i32_e32 v153, 31, v152
	v_lshlrev_b64 v[180:181], 1, v[152:153]
	v_ashrrev_i32_e32 v155, 31, v154
	v_lshl_add_u64 v[156:157], s[44:45], 0, v[180:181]
	v_lshlrev_b64 v[182:183], 11, v[154:155]
	v_lshl_add_u64 v[128:129], v[156:157], 0, v[182:183]
	v_mov_b64_e32 v[252:253], v[128:129]
	global_load_dwordx4 v[172:175], v[128:129], off
	global_load_dwordx4 v[176:179], v[128:129], off offset:256
	v_or_b32_e32 v158, 16, v154
	v_ashrrev_i32_e32 v159, 31, v158
	v_lshlrev_b64 v[160:161], 11, v[158:159]
	v_lshl_add_u64 v[128:129], v[156:157], 0, v[160:161]
	global_load_dwordx4 v[132:135], v[128:129], off
	s_nop 0
	global_load_dwordx4 v[128:131], v[128:129], off offset:256
	s_mov_b32 s100, 0x10000
	s_mov_b32 s101, 0
	v_lshl_add_u64 v[254:255], v[252:253], 0, s[100:101]
	global_load_dwordx4 v[200:203], v[254:255], off
	global_load_dwordx4 v[204:207], v[254:255], off offset:256
	s_mov_b32 s100, 0x18000
	s_mov_b32 s101, 0
	v_lshl_add_u64 v[254:255], v[252:253], 0, s[100:101]
	global_load_dwordx4 v[208:211], v[254:255], off
	global_load_dwordx4 v[212:215], v[254:255], off offset:256
	s_mov_b32 s100, 0x40000
	s_mov_b32 s101, 0
	v_lshl_add_u64 v[254:255], v[252:253], 0, s[100:101]
	global_load_dwordx4 v[216:219], v[254:255], off
	global_load_dwordx4 v[220:223], v[254:255], off offset:256
	s_mov_b32 s100, 0x48000
	s_mov_b32 s101, 0
	v_lshl_add_u64 v[254:255], v[252:253], 0, s[100:101]
	global_load_dwordx4 v[224:227], v[254:255], off
	global_load_dwordx4 v[228:231], v[254:255], off offset:256
	s_mov_b32 s100, 0x50000
	s_mov_b32 s101, 0
	v_lshl_add_u64 v[254:255], v[252:253], 0, s[100:101]
	global_load_dwordx4 v[232:235], v[254:255], off
	global_load_dwordx4 v[236:239], v[254:255], off offset:256
	s_mov_b32 s100, 0x58000
	s_mov_b32 s101, 0
	v_lshl_add_u64 v[254:255], v[252:253], 0, s[100:101]
	global_load_dwordx4 v[240:243], v[254:255], off
	global_load_dwordx4 v[248:251], v[254:255], off offset:256
	v_and_b32_e32 v170, 64, v168
	v_xor_b32_e32 v169, 16, v168
	v_add_u32_e32 v170, 64, v170
	v_xor_b32_e32 v171, 32, v168
	v_cmp_lt_i32_e32 vcc, v169, v170
	s_lshl_b32 s22, s6, 2
	s_ashr_i32 s23, s22, 31
	v_cndmask_b32_e32 v169, v168, v169, vcc
	v_cmp_lt_i32_e32 vcc, v171, v170
	v_lshlrev_b32_e32 v170, 2, v169
	s_waitcnt vmcnt(12)
	v_lshlrev_b32_e32 v184, 16, v172
	v_and_b32_e32 v185, 0xffff0000, v172
	v_lshlrev_b32_e32 v172, 16, v173
	v_and_b32_e32 v173, 0xffff0000, v173
	v_lshlrev_b32_e32 v186, 16, v174
	v_and_b32_e32 v187, 0xffff0000, v174
	v_lshlrev_b32_e32 v174, 16, v175
	v_and_b32_e32 v175, 0xffff0000, v175
	v_lshlrev_b32_e32 v188, 16, v176
	v_and_b32_e32 v189, 0xffff0000, v176
	v_lshlrev_b32_e32 v176, 16, v177
	v_and_b32_e32 v177, 0xffff0000, v177
	v_lshlrev_b32_e32 v190, 16, v178
	v_and_b32_e32 v191, 0xffff0000, v178
	v_lshlrev_b32_e32 v178, 16, v179
	v_and_b32_e32 v179, 0xffff0000, v179
	v_cndmask_b32_e32 v171, v168, v171, vcc
	v_pk_add_f32 v[126:127], v[126:127], v[172:173]
	v_pk_add_f32 v[124:125], v[124:125], v[184:185]
	v_pk_add_f32 v[122:123], v[122:123], v[174:175]
	v_pk_add_f32 v[120:121], v[120:121], v[186:187]
	v_pk_add_f32 v[118:119], v[118:119], v[176:177]
	v_pk_add_f32 v[116:117], v[116:117], v[188:189]
	v_pk_add_f32 v[172:173], v[114:115], v[178:179]
	v_pk_add_f32 v[174:175], v[112:113], v[190:191]
	v_lshlrev_b32_e32 v169, 2, v171
	v_cvt_pk_bf16_f32 v112, v124, v125
	v_cvt_pk_bf16_f32 v113, v126, v127
	v_cvt_pk_bf16_f32 v114, v120, v121
	v_cvt_pk_bf16_f32 v115, v122, v123
	v_mul_f32_e32 v125, v125, v125
	v_mul_f32_e32 v127, v127, v127
	v_mul_f32_e32 v121, v121, v121
	v_mul_f32_e32 v123, v123, v123
	v_mul_f32_e32 v171, v117, v117
	v_mul_f32_e32 v176, v119, v119
	v_mul_f32_e32 v177, v175, v175
	v_mul_f32_e32 v178, v173, v173
	v_fmac_f32_e32 v125, v124, v124
	v_fmac_f32_e32 v127, v126, v126
	v_fmac_f32_e32 v121, v120, v120
	v_fmac_f32_e32 v123, v122, v122
	v_fmac_f32_e32 v171, v116, v116
	v_fmac_f32_e32 v176, v118, v118
	v_fmac_f32_e32 v177, v174, v174
	v_fmac_f32_e32 v178, v172, v172
	v_add_f32_e32 v120, v125, v127
	v_add_f32_e32 v121, v121, v123
	v_add_f32_e32 v122, v171, v176
	v_add_f32_e32 v123, v177, v178
	v_add_f32_e32 v120, v120, v121
	v_add_f32_e32 v121, v122, v123
	v_add_f32_e32 v122, v120, v121
	ds_bpermute_b32 v123, v170, v122
	v_lshl_add_u64 v[120:121], s[44:45], 0, v[182:183]
	v_lshl_add_u64 v[120:121], v[120:121], 0, v[180:181]
	global_store_dwordx4 v[120:121], v[112:115], off
	s_waitcnt lgkmcnt(0)
	s_nop 0
	v_add_f32_e32 v112, v122, v123
	ds_bpermute_b32 v113, v169, v112
	v_cvt_pk_bf16_f32 v114, v116, v117
	v_cvt_pk_bf16_f32 v115, v118, v119
	v_cvt_pk_bf16_f32 v116, v174, v175
	v_cvt_pk_bf16_f32 v117, v172, v173
	global_store_dwordx4 v[120:121], v[114:117], off offset:256
	s_and_saveexec_b64 s[24:25], s[0:1]
	s_cbranch_execz .LBB0_774
	v_lshlrev_b64 v[114:115], 6, v[154:155]
	v_lshl_add_u64 v[114:115], s[48:49], 0, v[114:115]
	v_lshl_add_u64 v[114:115], s[22:23], 2, v[114:115]
	s_lshl_b32 s6, s41, 2
	v_lshl_add_u64 v[114:115], v[114:115], 0, s[6:7]
	s_waitcnt lgkmcnt(0)
	v_add_f32_e32 v112, v112, v113
	global_store_dword v[114:115], v112, off

; __device__ __forceinline__ unsigned cvt_pk_bf16(float lo, float hi) { unsigned r; asm volatile("v_cvt_pk_bf16_f32 %0, %1, %2" : "=v"(r) : "v"(lo), "v"(hi)); return r; }
; __device__ __forceinline__ unsigned cvt_pk_bf16(float lo, float hi) { f32x2_t v = {lo, hi}; bf16x2_t b = __builtin_convertvector(v, bf16x2_t); return __builtin_bit_cast(unsigned, b); }
;     __device__ __forceinline__ void operator()(const f32x4 (&acc)[2][2][4][2], const pg8::Unit& u, int wr, int wc, int fr, int fq) const {
;     ...
;                     for (int bj = 0; bj < 2; ++bj) { const size_t off = (size_t)(row0 + ai * 128 + (2 * mp + mq) * 16) * D + col0 + bj * 128;
;                         if (RB) { const u32x4 r = *(const u32x4*)(resb + off);
;                             x[mq][bj][0] = (f32x4){__builtin_bit_cast(float, r.x << 16), __builtin_bit_cast(float, r.x & 0xffff0000u), __builtin_bit_cast(float, r.y << 16), __builtin_bit_cast(float, r.y & 0xffff0000u)};
;                             x[mq][bj][1] = (f32x4){__builtin_bit_cast(float, r.z << 16), __builtin_bit_cast(float, r.z & 0xffff0000u), __builtin_bit_cast(float, r.w << 16), __builtin_bit_cast(float, r.w & 0xffff0000u)}; }
;                         else { x[mq][bj][0] = *(const f32x4*)(rb + off); x[mq][bj][1] = *(const f32x4*)(rb + off + 4); } }
; #pragma unroll
;                 for (int mq = 0; mq < 2; ++mq) { const int m = 2 * mp + mq, row = row0 + ai * 128 + m * 16; float ss = 0.f;
; #pragma unroll
;                     for (int bj = 0; bj < 2; ++bj) { const size_t off = (size_t)row * D + col0 + bj * 128;
;                         const f32x4 v0 = x[mq][bj][0] + acc[ai][bj][m][0] * scale, v1 = x[mq][bj][1] + acc[ai][bj][m][1] * scale;
;                         if (OF) { *(f32x4*)(out + off) = v0; *(f32x4*)(out + off + 4) = v1; }
;                         if (OB) { u32x4 w; w.x = cvt_pk_bf16(v0[0], v0[1]); w.y = cvt_pk_bf16(v0[2], v0[3]); w.z = cvt_pk_bf16(v1[0], v1[1]); w.w = cvt_pk_bf16(v1[2], v1[3]); *(u32x4*)(outb + off) = w; }
;                         if (WS) ss += ((v0[0] * v0[0] + v0[1] * v0[1]) + (v0[2] * v0[2] + v0[3] * v0[3])) + ((v1[0] * v1[0] + v1[1] * v1[1]) + (v1[2] * v1[2] + v1[3] * v1[3])); }
;                     if (WS) { ss += __shfl_xor(ss, 16); ss += __shfl_xor(ss, 32); if (fq == 0) ssq[(size_t)row * 16 + u.pn * 4 + wc] = ss; } }
.LBB0_776:
	s_or_b64 exec, exec, s[24:25]
	v_or_b32_e32 v108, 32, v154
	v_ashrrev_i32_e32 v109, 31, v108
	v_lshlrev_b64 v[118:119], 11, v[108:109]
	s_waitcnt lgkmcnt(0)
	v_lshl_add_u64 v[96:97], v[156:157], 0, v[118:119]
	v_or_b32_e32 v104, 48, v154
	v_ashrrev_i32_e32 v105, 31, v104
	v_lshlrev_b64 v[106:107], 11, v[104:105]
	v_lshl_add_u64 v[96:97], v[156:157], 0, v[106:107]
	s_waitcnt vmcnt(14)
	v_lshlrev_b32_e32 v120, 16, v200
	v_and_b32_e32 v121, 0xffff0000, v200
	v_lshlrev_b32_e32 v110, 16, v201
	v_and_b32_e32 v111, 0xffff0000, v201
	v_lshlrev_b32_e32 v122, 16, v202
	v_and_b32_e32 v123, 0xffff0000, v202
	v_lshlrev_b32_e32 v112, 16, v203
	v_and_b32_e32 v113, 0xffff0000, v203
	v_lshlrev_b32_e32 v124, 16, v204
	v_and_b32_e32 v125, 0xffff0000, v204
	v_lshlrev_b32_e32 v114, 16, v205
	v_and_b32_e32 v115, 0xffff0000, v205
	v_lshlrev_b32_e32 v126, 16, v206
	v_and_b32_e32 v127, 0xffff0000, v206
	v_lshlrev_b32_e32 v116, 16, v207
	v_and_b32_e32 v117, 0xffff0000, v207
	v_pk_add_f32 v[94:95], v[94:95], v[110:111]
	v_pk_add_f32 v[92:93], v[92:93], v[120:121]
	v_pk_add_f32 v[90:91], v[90:91], v[112:113]
	v_pk_add_f32 v[88:89], v[88:89], v[122:123]
	v_pk_add_f32 v[86:87], v[86:87], v[114:115]
	v_pk_add_f32 v[84:85], v[84:85], v[124:125]
	v_pk_add_f32 v[110:111], v[82:83], v[116:117]
	v_pk_add_f32 v[112:113], v[80:81], v[126:127]
	v_cvt_pk_bf16_f32 v80, v92, v93
	v_cvt_pk_bf16_f32 v81, v94, v95
	v_cvt_pk_bf16_f32 v82, v88, v89
	v_cvt_pk_bf16_f32 v83, v90, v91
	v_mul_f32_e32 v93, v93, v93
	v_mul_f32_e32 v95, v95, v95
	v_mul_f32_e32 v89, v89, v89
	v_mul_f32_e32 v91, v91, v91
	v_mul_f32_e32 v114, v85, v85
	v_mul_f32_e32 v115, v87, v87
	v_mul_f32_e32 v116, v113, v113
	v_mul_f32_e32 v117, v111, v111
	v_fmac_f32_e32 v93, v92, v92
	v_fmac_f32_e32 v95, v94, v94
	v_fmac_f32_e32 v89, v88, v88
	v_fmac_f32_e32 v91, v90, v90
	v_fmac_f32_e32 v114, v84, v84
	v_fmac_f32_e32 v115, v86, v86
	v_fmac_f32_e32 v116, v112, v112
	v_fmac_f32_e32 v117, v110, v110
	v_add_f32_e32 v88, v93, v95
	v_add_f32_e32 v89, v89, v91
	v_add_f32_e32 v90, v114, v115
	v_add_f32_e32 v91, v116, v117
	v_add_f32_e32 v88, v88, v89
	v_add_f32_e32 v89, v90, v91
	v_add_f32_e32 v90, v88, v89
	ds_bpermute_b32 v91, v170, v90
	v_lshl_add_u64 v[88:89], s[44:45], 0, v[118:119]
	v_lshl_add_u64 v[88:89], v[152:153], 1, v[88:89]
	global_store_dwordx4 v[88:89], v[80:83], off
	s_waitcnt lgkmcnt(0)
	s_nop 0
	v_add_f32_e32 v80, v90, v91
	ds_bpermute_b32 v81, v169, v80
	v_cvt_pk_bf16_f32 v82, v84, v85
	v_cvt_pk_bf16_f32 v83, v86, v87
	v_cvt_pk_bf16_f32 v84, v112, v113
	v_cvt_pk_bf16_f32 v85, v110, v111
	global_store_dwordx4 v[88:89], v[82:85], off offset:256
	s_and_saveexec_b64 s[24:25], s[0:1]
	s_cbranch_execz .LBB0_778
	v_lshlrev_b64 v[82:83], 6, v[108:109]
	v_lshl_add_u64 v[82:83], s[48:49], 0, v[82:83]
	v_lshl_add_u64 v[82:83], s[22:23], 2, v[82:83]
	s_lshl_b32 s6, s41, 2
	v_lshl_add_u64 v[82:83], v[82:83], 0, s[6:7]
	s_waitcnt lgkmcnt(0)
	v_add_f32_e32 v80, v80, v81
	global_store_dword v[82:83], v80, off
.LBB0_778:
	s_or_b64 exec, exec, s[24:25]
	v_lshlrev_b32_e32 v80, 16, v208
	s_waitcnt lgkmcnt(0)
	v_and_b32_e32 v81, 0xffff0000, v208
	v_lshlrev_b32_e32 v82, 16, v209
	v_and_b32_e32 v83, 0xffff0000, v209
	v_lshlrev_b32_e32 v84, 16, v210
	v_and_b32_e32 v85, 0xffff0000, v210
	v_pk_add_f32 v[76:77], v[76:77], v[80:81]
	v_pk_add_f32 v[78:79], v[78:79], v[82:83]
	v_pk_add_f32 v[82:83], v[72:73], v[84:85]
	v_cvt_pk_bf16_f32 v72, v76, v77
	v_mul_f32_e32 v77, v77, v77
	v_lshlrev_b32_e32 v86, 16, v211
	v_and_b32_e32 v87, 0xffff0000, v211
	v_fmac_f32_e32 v77, v76, v76
	v_mul_f32_e32 v76, v79, v79
	v_pk_add_f32 v[80:81], v[74:75], v[86:87]
	v_fmac_f32_e32 v76, v78, v78
	v_lshlrev_b32_e32 v88, 16, v212
	v_and_b32_e32 v89, 0xffff0000, v212
	v_lshlrev_b32_e32 v90, 16, v213
	v_and_b32_e32 v91, 0xffff0000, v213
	v_cvt_pk_bf16_f32 v73, v78, v79
	v_add_f32_e32 v76, v77, v76
	v_mul_f32_e32 v77, v83, v83
	v_mul_f32_e32 v78, v81, v81
	v_lshlrev_b32_e32 v92, 16, v214
	v_and_b32_e32 v93, 0xffff0000, v214
	v_fmac_f32_e32 v77, v82, v82
	v_fmac_f32_e32 v78, v80, v80
	v_pk_add_f32 v[70:71], v[70:71], v[90:91]
	v_pk_add_f32 v[68:69], v[68:69], v[88:89]
	v_lshlrev_b32_e32 v94, 16, v215
	v_and_b32_e32 v95, 0xffff0000, v215
	v_add_f32_e32 v77, v77, v78
	v_pk_add_f32 v[78:79], v[64:65], v[92:93]
	v_mul_f32_e32 v64, v69, v69
	v_mul_f32_e32 v65, v71, v71
	v_cvt_pk_bf16_f32 v75, v80, v81
	v_add_f32_e32 v80, v76, v77
	v_pk_add_f32 v[76:77], v[66:67], v[94:95]
	v_fmac_f32_e32 v64, v68, v68
	v_fmac_f32_e32 v65, v70, v70
	v_add_f32_e32 v64, v64, v65
	v_mul_f32_e32 v65, v79, v79
	v_mul_f32_e32 v66, v77, v77
	v_fmac_f32_e32 v65, v78, v78
	v_fmac_f32_e32 v66, v76, v76
	v_add_f32_e32 v65, v65, v66
	v_add_f32_e32 v64, v64, v65
	v_add_f32_e32 v67, v80, v64
	v_cvt_pk_bf16_f32 v74, v82, v83
	ds_bpermute_b32 v82, v170, v67
	v_lshl_add_u64 v[64:65], s[44:45], 0, v[106:107]
	v_lshl_add_u64 v[80:81], v[152:153], 1, v[64:65]
	v_cvt_pk_bf16_f32 v66, v68, v69
	v_cvt_pk_bf16_f32 v68, v78, v79
	s_waitcnt lgkmcnt(0)
	v_add_f32_e32 v64, v67, v82
	ds_bpermute_b32 v65, v169, v64
	v_cvt_pk_bf16_f32 v67, v70, v71
	v_cvt_pk_bf16_f32 v69, v76, v77
	global_store_dwordx4 v[80:81], v[72:75], off
	global_store_dwordx4 v[80:81], v[66:69], off offset:256
	s_and_saveexec_b64 s[24:25], s[0:1]
	s_cbranch_execz .LBB0_780
	v_lshlrev_b64 v[66:67], 6, v[104:105]
	v_lshl_add_u64 v[66:67], s[48:49], 0, v[66:67]
	v_lshl_add_u64 v[66:67], s[22:23], 2, v[66:67]
	s_lshl_b32 s6, s41, 2
	v_lshl_add_u64 v[66:67], v[66:67], 0, s[6:7]
	s_waitcnt lgkmcnt(0)
	v_add_f32_e32 v64, v64, v65
	global_store_dword v[66:67], v64, off
; __device__ __forceinline__ unsigned cvt_pk_bf16(float lo, float hi) { unsigned r; asm volatile("v_cvt_pk_bf16_f32 %0, %1, %2" : "=v"(r) : "v"(lo), "v"(hi)); return r; }
; __device__ __forceinline__ unsigned cvt_pk_bf16(float lo, float hi) { f32x2_t v = {lo, hi}; bf16x2_t b = __builtin_convertvector(v, bf16x2_t); return __builtin_bit_cast(unsigned, b); }
;     __device__ __forceinline__ void operator()(const f32x4 (&acc)[2][2][4][2], const pg8::Unit& u, int wr, int wc, int fr, int fq) const {
;     ...
;                     for (int bj = 0; bj < 2; ++bj) { const size_t off = (size_t)(row0 + ai * 128 + (2 * mp + mq) * 16) * D + col0 + bj * 128;
;                         if (RB) { const u32x4 r = *(const u32x4*)(resb + off);
;                             x[mq][bj][0] = (f32x4){__builtin_bit_cast(float, r.x << 16), __builtin_bit_cast(float, r.x & 0xffff0000u), __builtin_bit_cast(float, r.y << 16), __builtin_bit_cast(float, r.y & 0xffff0000u)};
;                             x[mq][bj][1] = (f32x4){__builtin_bit_cast(float, r.z << 16), __builtin_bit_cast(float, r.z & 0xffff0000u), __builtin_bit_cast(float, r.w << 16), __builtin_bit_cast(float, r.w & 0xffff0000u)}; }
;                         else { x[mq][bj][0] = *(const f32x4*)(rb + off); x[mq][bj][1] = *(const f32x4*)(rb + off + 4); } }
; #pragma unroll
;                 for (int mq = 0; mq < 2; ++mq) { const int m = 2 * mp + mq, row = row0 + ai * 128 + m * 16; float ss = 0.f;
; #pragma unroll
;                     for (int bj = 0; bj < 2; ++bj) { const size_t off = (size_t)row * D + col0 + bj * 128;
;                         const f32x4 v0 = x[mq][bj][0] + acc[ai][bj][m][0] * scale, v1 = x[mq][bj][1] + acc[ai][bj][m][1] * scale;
;                         if (OF) { *(f32x4*)(out + off) = v0; *(f32x4*)(out + off + 4) = v1; }
;                         if (OB) { u32x4 w; w.x = cvt_pk_bf16(v0[0], v0[1]); w.y = cvt_pk_bf16(v0[2], v0[3]); w.z = cvt_pk_bf16(v1[0], v1[1]); w.w = cvt_pk_bf16(v1[2], v1[3]); *(u32x4*)(outb + off) = w; }
;                         if (WS) ss += ((v0[0] * v0[0] + v0[1] * v0[1]) + (v0[2] * v0[2] + v0[3] * v0[3])) + ((v1[0] * v1[0] + v1[1] * v1[1]) + (v1[2] * v1[2] + v1[3] * v1[3])); }
;                     if (WS) { ss += __shfl_xor(ss, 16); ss += __shfl_xor(ss, 32); if (fq == 0) ssq[(size_t)row * 16 + u.pn * 4 + wc] = ss; } }
.LBB0_780:
	s_or_b64 exec, exec, s[24:25]
	v_add_u32_e32 v76, 0x80, v154
	v_ashrrev_i32_e32 v77, 31, v76
	v_lshlrev_b64 v[86:87], 11, v[76:77]
	s_waitcnt lgkmcnt(0)
	v_lshl_add_u64 v[64:65], v[156:157], 0, v[86:87]
	v_add_u32_e32 v72, 0x90, v154
	v_ashrrev_i32_e32 v73, 31, v72
	v_lshlrev_b64 v[74:75], 11, v[72:73]
	v_lshl_add_u64 v[64:65], v[156:157], 0, v[74:75]
	s_waitcnt vmcnt(16)
	v_lshlrev_b32_e32 v88, 16, v216
	v_and_b32_e32 v89, 0xffff0000, v216
	v_lshlrev_b32_e32 v78, 16, v217
	v_and_b32_e32 v79, 0xffff0000, v217
	v_lshlrev_b32_e32 v90, 16, v218
	v_and_b32_e32 v91, 0xffff0000, v218
	v_lshlrev_b32_e32 v80, 16, v219
	v_and_b32_e32 v81, 0xffff0000, v219
	v_lshlrev_b32_e32 v92, 16, v220
	v_and_b32_e32 v93, 0xffff0000, v220
	v_lshlrev_b32_e32 v82, 16, v221
	v_and_b32_e32 v83, 0xffff0000, v221
	v_lshlrev_b32_e32 v94, 16, v222
	v_and_b32_e32 v95, 0xffff0000, v222
	v_lshlrev_b32_e32 v84, 16, v223
	v_and_b32_e32 v85, 0xffff0000, v223
	v_pk_add_f32 v[62:63], v[62:63], v[78:79]
	v_pk_add_f32 v[60:61], v[60:61], v[88:89]
	v_pk_add_f32 v[58:59], v[58:59], v[80:81]
	v_pk_add_f32 v[56:57], v[56:57], v[90:91]
	v_pk_add_f32 v[54:55], v[54:55], v[82:83]
	v_pk_add_f32 v[52:53], v[52:53], v[92:93]
	v_pk_add_f32 v[78:79], v[50:51], v[84:85]
	v_pk_add_f32 v[80:81], v[48:49], v[94:95]
	v_cvt_pk_bf16_f32 v48, v60, v61
	v_cvt_pk_bf16_f32 v49, v62, v63
	v_cvt_pk_bf16_f32 v50, v56, v57
	v_cvt_pk_bf16_f32 v51, v58, v59
	v_mul_f32_e32 v61, v61, v61
	v_mul_f32_e32 v63, v63, v63
	v_mul_f32_e32 v57, v57, v57
	v_mul_f32_e32 v59, v59, v59
	v_mul_f32_e32 v82, v53, v53
	v_mul_f32_e32 v83, v55, v55
	v_mul_f32_e32 v84, v81, v81
	v_mul_f32_e32 v85, v79, v79
	v_fmac_f32_e32 v61, v60, v60
	v_fmac_f32_e32 v63, v62, v62
	v_fmac_f32_e32 v57, v56, v56
	v_fmac_f32_e32 v59, v58, v58
	v_fmac_f32_e32 v82, v52, v52
	v_fmac_f32_e32 v83, v54, v54
	v_fmac_f32_e32 v84, v80, v80
	v_fmac_f32_e32 v85, v78, v78
	v_add_f32_e32 v56, v61, v63
	v_add_f32_e32 v57, v57, v59
	v_add_f32_e32 v58, v82, v83
	v_add_f32_e32 v59, v84, v85
	v_add_f32_e32 v56, v56, v57
	v_add_f32_e32 v57, v58, v59
	v_add_f32_e32 v58, v56, v57
	ds_bpermute_b32 v59, v170, v58
	v_lshl_add_u64 v[56:57], s[44:45], 0, v[86:87]
	v_lshl_add_u64 v[56:57], v[152:153], 1, v[56:57]
	global_store_dwordx4 v[56:57], v[48:51], off
	s_waitcnt lgkmcnt(0)
	s_nop 0
	v_add_f32_e32 v48, v58, v59
	ds_bpermute_b32 v49, v169, v48
	v_cvt_pk_bf16_f32 v50, v52, v53
	v_cvt_pk_bf16_f32 v51, v54, v55
	v_cvt_pk_bf16_f32 v52, v80, v81
	v_cvt_pk_bf16_f32 v53, v78, v79
	global_store_dwordx4 v[56:57], v[50:53], off offset:256
	s_and_saveexec_b64 s[24:25], s[0:1]
	s_cbranch_execz .LBB0_782
	v_lshlrev_b64 v[50:51], 6, v[76:77]
	v_lshl_add_u64 v[50:51], s[48:49], 0, v[50:51]
	v_lshl_add_u64 v[50:51], s[22:23], 2, v[50:51]
	s_lshl_b32 s6, s41, 2
	v_lshl_add_u64 v[50:51], v[50:51], 0, s[6:7]
	s_waitcnt lgkmcnt(0)
	v_add_f32_e32 v48, v48, v49
	global_store_dword v[50:51], v48, off
.LBB0_782:
	s_or_b64 exec, exec, s[24:25]
	v_lshlrev_b32_e32 v48, 16, v224
	s_waitcnt lgkmcnt(0)
	v_and_b32_e32 v49, 0xffff0000, v224
	v_lshlrev_b32_e32 v50, 16, v225
	v_and_b32_e32 v51, 0xffff0000, v225
	v_lshlrev_b32_e32 v52, 16, v226
	v_and_b32_e32 v53, 0xffff0000, v226
	v_pk_add_f32 v[44:45], v[44:45], v[48:49]
	v_pk_add_f32 v[46:47], v[46:47], v[50:51]
	v_pk_add_f32 v[50:51], v[40:41], v[52:53]
	v_cvt_pk_bf16_f32 v40, v44, v45
	v_mul_f32_e32 v45, v45, v45
	v_lshlrev_b32_e32 v54, 16, v227
	v_and_b32_e32 v55, 0xffff0000, v227
	v_fmac_f32_e32 v45, v44, v44
	v_mul_f32_e32 v44, v47, v47
	v_pk_add_f32 v[48:49], v[42:43], v[54:55]
	v_fmac_f32_e32 v44, v46, v46
	v_lshlrev_b32_e32 v56, 16, v228
	v_and_b32_e32 v57, 0xffff0000, v228
	v_lshlrev_b32_e32 v58, 16, v229
	v_and_b32_e32 v59, 0xffff0000, v229
	v_cvt_pk_bf16_f32 v41, v46, v47
	v_add_f32_e32 v44, v45, v44
	v_mul_f32_e32 v45, v51, v51
	v_mul_f32_e32 v46, v49, v49
	v_lshlrev_b32_e32 v60, 16, v230
	v_and_b32_e32 v61, 0xffff0000, v230
	v_fmac_f32_e32 v45, v50, v50
	v_fmac_f32_e32 v46, v48, v48
	v_pk_add_f32 v[38:39], v[38:39], v[58:59]
	v_pk_add_f32 v[36:37], v[36:37], v[56:57]
	v_lshlrev_b32_e32 v62, 16, v231
	v_and_b32_e32 v63, 0xffff0000, v231
	v_add_f32_e32 v45, v45, v46
	v_pk_add_f32 v[46:47], v[32:33], v[60:61]
	v_mul_f32_e32 v32, v37, v37
	v_mul_f32_e32 v33, v39, v39
	v_cvt_pk_bf16_f32 v43, v48, v49
	v_add_f32_e32 v48, v44, v45
	v_pk_add_f32 v[44:45], v[34:35], v[62:63]
	v_fmac_f32_e32 v32, v36, v36
	v_fmac_f32_e32 v33, v38, v38
	v_add_f32_e32 v32, v32, v33
	v_mul_f32_e32 v33, v47, v47
	v_mul_f32_e32 v34, v45, v45
	v_fmac_f32_e32 v33, v46, v46
	v_fmac_f32_e32 v34, v44, v44
	v_add_f32_e32 v33, v33, v34
	v_add_f32_e32 v32, v32, v33
	v_add_f32_e32 v35, v48, v32
	v_cvt_pk_bf16_f32 v42, v50, v51
	ds_bpermute_b32 v50, v170, v35
	v_lshl_add_u64 v[32:33], s[44:45], 0, v[74:75]
	v_lshl_add_u64 v[48:49], v[152:153], 1, v[32:33]
	v_cvt_pk_bf16_f32 v34, v36, v37
	v_cvt_pk_bf16_f32 v36, v46, v47
	s_waitcnt lgkmcnt(0)
	v_add_f32_e32 v32, v35, v50
	ds_bpermute_b32 v33, v169, v32
	v_cvt_pk_bf16_f32 v35, v38, v39
	v_cvt_pk_bf16_f32 v37, v44, v45
	global_store_dwordx4 v[48:49], v[40:43], off
	global_store_dwordx4 v[48:49], v[34:37], off offset:256
	s_and_saveexec_b64 s[24:25], s[0:1]
	s_cbranch_execz .LBB0_784
	v_lshlrev_b64 v[34:35], 6, v[72:73]
	v_lshl_add_u64 v[34:35], s[48:49], 0, v[34:35]
	v_lshl_add_u64 v[34:35], s[22:23], 2, v[34:35]
	s_lshl_b32 s6, s41, 2
	v_lshl_add_u64 v[34:35], v[34:35], 0, s[6:7]
	s_waitcnt lgkmcnt(0)
	v_add_f32_e32 v32, v32, v33
	global_store_dword v[34:35], v32, off
; __device__ __forceinline__ unsigned cvt_pk_bf16(float lo, float hi) { unsigned r; asm volatile("v_cvt_pk_bf16_f32 %0, %1, %2" : "=v"(r) : "v"(lo), "v"(hi)); return r; }
; __device__ __forceinline__ unsigned cvt_pk_bf16(float lo, float hi) { f32x2_t v = {lo, hi}; bf16x2_t b = __builtin_convertvector(v, bf16x2_t); return __builtin_bit_cast(unsigned, b); }
;     __device__ __forceinline__ void operator()(const f32x4 (&acc)[2][2][4][2], const pg8::Unit& u, int wr, int wc, int fr, int fq) const {
;     ...
;                     for (int bj = 0; bj < 2; ++bj) { const size_t off = (size_t)(row0 + ai * 128 + (2 * mp + mq) * 16) * D + col0 + bj * 128;
;                         if (RB) { const u32x4 r = *(const u32x4*)(resb + off);
;                             x[mq][bj][0] = (f32x4){__builtin_bit_cast(float, r.x << 16), __builtin_bit_cast(float, r.x & 0xffff0000u), __builtin_bit_cast(float, r.y << 16), __builtin_bit_cast(float, r.y & 0xffff0000u)};
;                             x[mq][bj][1] = (f32x4){__builtin_bit_cast(float, r.z << 16), __builtin_bit_cast(float, r.z & 0xffff0000u), __builtin_bit_cast(float, r.w << 16), __builtin_bit_cast(float, r.w & 0xffff0000u)}; }
;                         else { x[mq][bj][0] = *(const f32x4*)(rb + off); x[mq][bj][1] = *(const f32x4*)(rb + off + 4); } }
; #pragma unroll
;                 for (int mq = 0; mq < 2; ++mq) { const int m = 2 * mp + mq, row = row0 + ai * 128 + m * 16; float ss = 0.f;
; #pragma unroll
;                     for (int bj = 0; bj < 2; ++bj) { const size_t off = (size_t)row * D + col0 + bj * 128;
;                         const f32x4 v0 = x[mq][bj][0] + acc[ai][bj][m][0] * scale, v1 = x[mq][bj][1] + acc[ai][bj][m][1] * scale;
;                         if (OF) { *(f32x4*)(out + off) = v0; *(f32x4*)(out + off + 4) = v1; }
;                         if (OB) { u32x4 w; w.x = cvt_pk_bf16(v0[0], v0[1]); w.y = cvt_pk_bf16(v0[2], v0[3]); w.z = cvt_pk_bf16(v1[0], v1[1]); w.w = cvt_pk_bf16(v1[2], v1[3]); *(u32x4*)(outb + off) = w; }
;                         if (WS) ss += ((v0[0] * v0[0] + v0[1] * v0[1]) + (v0[2] * v0[2] + v0[3] * v0[3])) + ((v1[0] * v1[0] + v1[1] * v1[1]) + (v1[2] * v1[2] + v1[3] * v1[3])); }
;                     if (WS) { ss += __shfl_xor(ss, 16); ss += __shfl_xor(ss, 32); if (fq == 0) ssq[(size_t)row * 16 + u.pn * 4 + wc] = ss; } }
.LBB0_784:
	s_or_b64 exec, exec, s[24:25]
	v_add_u32_e32 v44, 0xa0, v154
	v_ashrrev_i32_e32 v45, 31, v44
	v_lshlrev_b64 v[54:55], 11, v[44:45]
	s_waitcnt lgkmcnt(0)
	v_lshl_add_u64 v[32:33], v[156:157], 0, v[54:55]
	v_add_u32_e32 v40, 0xb0, v154
	v_ashrrev_i32_e32 v41, 31, v40
	v_lshlrev_b64 v[42:43], 11, v[40:41]
	v_lshl_add_u64 v[32:33], v[156:157], 0, v[42:43]
	s_waitcnt vmcnt(18)
	v_lshlrev_b32_e32 v56, 16, v232
	v_and_b32_e32 v57, 0xffff0000, v232
	v_lshlrev_b32_e32 v46, 16, v233
	v_and_b32_e32 v47, 0xffff0000, v233
	v_lshlrev_b32_e32 v58, 16, v234
	v_and_b32_e32 v59, 0xffff0000, v234
	v_lshlrev_b32_e32 v48, 16, v235
	v_and_b32_e32 v49, 0xffff0000, v235
	v_lshlrev_b32_e32 v60, 16, v236
	v_and_b32_e32 v61, 0xffff0000, v236
	v_lshlrev_b32_e32 v50, 16, v237
	v_and_b32_e32 v51, 0xffff0000, v237
	v_lshlrev_b32_e32 v62, 16, v238
	v_and_b32_e32 v63, 0xffff0000, v238
	v_lshlrev_b32_e32 v52, 16, v239
	v_and_b32_e32 v53, 0xffff0000, v239
	v_pk_add_f32 v[30:31], v[30:31], v[46:47]
	v_pk_add_f32 v[28:29], v[28:29], v[56:57]
	v_pk_add_f32 v[26:27], v[26:27], v[48:49]
	v_pk_add_f32 v[24:25], v[24:25], v[58:59]
	v_pk_add_f32 v[22:23], v[22:23], v[50:51]
	v_pk_add_f32 v[20:21], v[20:21], v[60:61]
	v_pk_add_f32 v[46:47], v[18:19], v[52:53]
	v_pk_add_f32 v[48:49], v[16:17], v[62:63]
	v_cvt_pk_bf16_f32 v16, v28, v29
	v_cvt_pk_bf16_f32 v17, v30, v31
	v_cvt_pk_bf16_f32 v18, v24, v25
	v_cvt_pk_bf16_f32 v19, v26, v27
	v_mul_f32_e32 v29, v29, v29
	v_mul_f32_e32 v31, v31, v31
	v_mul_f32_e32 v25, v25, v25
	v_mul_f32_e32 v27, v27, v27
	v_mul_f32_e32 v50, v21, v21
	v_mul_f32_e32 v51, v23, v23
	v_mul_f32_e32 v52, v49, v49
	v_mul_f32_e32 v53, v47, v47
	v_fmac_f32_e32 v29, v28, v28
	v_fmac_f32_e32 v31, v30, v30
	v_fmac_f32_e32 v25, v24, v24
	v_fmac_f32_e32 v27, v26, v26
	v_fmac_f32_e32 v50, v20, v20
	v_fmac_f32_e32 v51, v22, v22
	v_fmac_f32_e32 v52, v48, v48
	v_fmac_f32_e32 v53, v46, v46
	v_add_f32_e32 v24, v29, v31
	v_add_f32_e32 v25, v25, v27
	v_add_f32_e32 v26, v50, v51
	v_add_f32_e32 v27, v52, v53
	v_add_f32_e32 v24, v24, v25
	v_add_f32_e32 v25, v26, v27
	v_add_f32_e32 v26, v24, v25
	ds_bpermute_b32 v27, v170, v26
	v_lshl_add_u64 v[24:25], s[44:45], 0, v[54:55]
	v_lshl_add_u64 v[24:25], v[152:153], 1, v[24:25]
	global_store_dwordx4 v[24:25], v[16:19], off
	s_waitcnt lgkmcnt(0)
	s_nop 0
	v_add_f32_e32 v16, v26, v27
	ds_bpermute_b32 v17, v169, v16
	v_cvt_pk_bf16_f32 v18, v20, v21
	v_cvt_pk_bf16_f32 v19, v22, v23
	v_cvt_pk_bf16_f32 v20, v48, v49
	v_cvt_pk_bf16_f32 v21, v46, v47
	global_store_dwordx4 v[24:25], v[18:21], off offset:256
	s_and_saveexec_b64 s[24:25], s[0:1]
	s_cbranch_execz .LBB0_786
	v_lshlrev_b64 v[18:19], 6, v[44:45]
	v_lshl_add_u64 v[18:19], s[48:49], 0, v[18:19]
	v_lshl_add_u64 v[18:19], s[22:23], 2, v[18:19]
	s_lshl_b32 s6, s41, 2
	v_lshl_add_u64 v[18:19], v[18:19], 0, s[6:7]
	s_waitcnt lgkmcnt(0)
	v_add_f32_e32 v16, v16, v17
	global_store_dword v[18:19], v16, off
.LBB0_786:
	s_or_b64 exec, exec, s[24:25]
	v_lshlrev_b32_e32 v16, 16, v240
	s_waitcnt lgkmcnt(0)
	v_and_b32_e32 v17, 0xffff0000, v240
	v_lshlrev_b32_e32 v18, 16, v241
	v_and_b32_e32 v19, 0xffff0000, v241
	v_lshlrev_b32_e32 v20, 16, v242
	v_and_b32_e32 v21, 0xffff0000, v242
	v_pk_add_f32 v[12:13], v[12:13], v[16:17]
	v_pk_add_f32 v[14:15], v[14:15], v[18:19]
	v_pk_add_f32 v[18:19], v[8:9], v[20:21]
	v_cvt_pk_bf16_f32 v8, v12, v13
	v_mul_f32_e32 v13, v13, v13
	v_lshlrev_b32_e32 v22, 16, v243
	v_and_b32_e32 v23, 0xffff0000, v243
	v_fmac_f32_e32 v13, v12, v12
	v_mul_f32_e32 v12, v15, v15
	v_pk_add_f32 v[16:17], v[10:11], v[22:23]
	v_fmac_f32_e32 v12, v14, v14
	v_lshlrev_b32_e32 v24, 16, v248
	v_and_b32_e32 v25, 0xffff0000, v248
	v_lshlrev_b32_e32 v26, 16, v249
	v_and_b32_e32 v27, 0xffff0000, v249
	v_cvt_pk_bf16_f32 v9, v14, v15
	v_add_f32_e32 v12, v13, v12
	v_mul_f32_e32 v13, v19, v19
	v_mul_f32_e32 v14, v17, v17
	v_lshlrev_b32_e32 v28, 16, v250
	v_and_b32_e32 v29, 0xffff0000, v250
	v_fmac_f32_e32 v13, v18, v18
	v_fmac_f32_e32 v14, v16, v16
	v_pk_add_f32 v[6:7], v[6:7], v[26:27]
	v_pk_add_f32 v[4:5], v[4:5], v[24:25]
	v_lshlrev_b32_e32 v30, 16, v251
	v_and_b32_e32 v31, 0xffff0000, v251
	v_add_f32_e32 v13, v13, v14
	v_pk_add_f32 v[14:15], v[0:1], v[28:29]
	v_mul_f32_e32 v0, v5, v5
	v_mul_f32_e32 v1, v7, v7
	v_cvt_pk_bf16_f32 v11, v16, v17
	v_add_f32_e32 v16, v12, v13
	v_pk_add_f32 v[12:13], v[2:3], v[30:31]
	v_fmac_f32_e32 v0, v4, v4
	v_fmac_f32_e32 v1, v6, v6
	v_add_f32_e32 v0, v0, v1
	v_mul_f32_e32 v1, v15, v15
	v_mul_f32_e32 v2, v13, v13
	v_fmac_f32_e32 v1, v14, v14
	v_fmac_f32_e32 v2, v12, v12
	v_add_f32_e32 v1, v1, v2
	v_add_f32_e32 v0, v0, v1
	v_add_f32_e32 v3, v16, v0
	v_cvt_pk_bf16_f32 v10, v18, v19
	ds_bpermute_b32 v18, v170, v3
	v_lshl_add_u64 v[0:1], s[44:45], 0, v[42:43]
	v_lshl_add_u64 v[16:17], v[152:153], 1, v[0:1]
	v_cvt_pk_bf16_f32 v2, v4, v5
	v_cvt_pk_bf16_f32 v4, v14, v15
	s_waitcnt lgkmcnt(0)
	v_add_f32_e32 v0, v3, v18
	ds_bpermute_b32 v1, v169, v0
	v_cvt_pk_bf16_f32 v3, v6, v7
	v_cvt_pk_bf16_f32 v5, v12, v13
	global_store_dwordx4 v[16:17], v[8:11], off
	global_store_dwordx4 v[16:17], v[2:5], off offset:256
	s_and_saveexec_b64 s[24:25], s[0:1]
	s_cbranch_execz .LBB0_788
	v_lshlrev_b64 v[2:3], 6, v[40:41]
	v_lshl_add_u64 v[2:3], s[48:49], 0, v[2:3]
	v_lshl_add_u64 v[2:3], s[22:23], 2, v[2:3]
	s_lshl_b32 s6, s41, 2
	v_lshl_add_u64 v[2:3], v[2:3], 0, s[6:7]
	s_waitcnt lgkmcnt(0)
	v_add_f32_e32 v0, v0, v1
	global_store_dword v[2:3], v0, off

; #define LAS __attribute__((address_space(3)))
; __global__ void __launch_bounds__(NTHR, 2) mk_fwd(Params p) {
;     extern __shared__ __attribute__((aligned(16))) unsigned char lds_raw[];
;     LAS unsigned char* lds = (LAS unsigned char*)lds_raw;
;     const int G = gridDim.x, lo = p.ph_lo, hi = p.ph_hi;
	.amdhsa_kernel _Z6mk_fwd6Params
		.amdhsa_group_segment_fixed_size 0
		.amdhsa_private_segment_fixed_size 0
		.amdhsa_kernarg_size 424
		.amdhsa_user_sgpr_count 2
		.amdhsa_user_sgpr_dispatch_ptr 0
		.amdhsa_user_sgpr_queue_ptr 0
		.amdhsa_user_sgpr_kernarg_segment_ptr 1
		.amdhsa_user_sgpr_dispatch_id 0
		.amdhsa_user_sgpr_kernarg_preload_length 0
		.amdhsa_user_sgpr_kernarg_preload_offset 0
		.amdhsa_user_sgpr_private_segment_size 0
		.amdhsa_uses_dynamic_stack 0
		.amdhsa_enable_private_segment 0
		.amdhsa_system_sgpr_workgroup_id_x 1
		.amdhsa_system_sgpr_workgroup_id_y 0
		.amdhsa_system_sgpr_workgroup_id_z 0
		.amdhsa_system_sgpr_workgroup_info 0
		.amdhsa_system_vgpr_workitem_id 2
		.amdhsa_next_free_vgpr 256
		.amdhsa_next_free_sgpr 102
		.amdhsa_accum_offset 256
		.amdhsa_reserve_vcc 1
		.amdhsa_float_round_mode_32 0
		.amdhsa_float_round_mode_16_64 0
		.amdhsa_float_denorm_mode_32 3
		.amdhsa_float_denorm_mode_16_64 3
		.amdhsa_dx10_clamp 1
		.amdhsa_ieee_mode 1
		.amdhsa_fp16_overflow 0
		.amdhsa_tg_split 0
		.amdhsa_exception_fp_ieee_invalid_op 0
		.amdhsa_exception_fp_denorm_src 0
		.amdhsa_exception_fp_ieee_div_zero 0
		.amdhsa_exception_fp_ieee_overflow 0
		.amdhsa_exception_fp_ieee_underflow 0
		.amdhsa_exception_fp_ieee_inexact 0
		.amdhsa_exception_int_div_zero 0
	.end_amdhsa_kernel

; #define LAS __attribute__((address_space(3)))
; __global__ void __launch_bounds__(NTHR, 2) mk_fwd(Params p) {
;     extern __shared__ __attribute__((aligned(16))) unsigned char lds_raw[];
;     LAS unsigned char* lds = (LAS unsigned char*)lds_raw;
;     const int G = gridDim.x, lo = p.ph_lo, hi = p.ph_hi;
.Lfunc_end0:
	.size	_Z6mk_fwd6Params, .Lfunc_end0-_Z6mk_fwd6Params
	.set _Z6mk_fwd6Params.num_vgpr, 256
	.set _Z6mk_fwd6Params.num_agpr, 0
	.set _Z6mk_fwd6Params.numbered_sgpr, 102
	.set _Z6mk_fwd6Params.num_named_barrier, 0
	.set _Z6mk_fwd6Params.private_seg_size, 0
	.set _Z6mk_fwd6Params.uses_vcc, 1
	.set _Z6mk_fwd6Params.uses_flat_scratch, 0
	.set _Z6mk_fwd6Params.has_dyn_sized_stack, 0
	.set _Z6mk_fwd6Params.has_recursion, 0
	.set _Z6mk_fwd6Params.has_indirect_call, 0

; #define LAS __attribute__((address_space(3)))
; __global__ void __launch_bounds__(NTHR, 2) mk_fwd(Params p) {
;     extern __shared__ __attribute__((aligned(16))) unsigned char lds_raw[];
;     LAS unsigned char* lds = (LAS unsigned char*)lds_raw;
;     const int G = gridDim.x, lo = p.ph_lo, hi = p.ph_hi;
amdhsa.kernels:
  - .agpr_count:     0
    .args:
      - .offset:         0
        .size:           168
        .value_kind:     by_value
      - .offset:         168
        .size:           4
        .value_kind:     hidden_block_count_x
      - .offset:         172
        .size:           4
        .value_kind:     hidden_block_count_y
      - .offset:         176
        .size:           4
        .value_kind:     hidden_block_count_z
      - .offset:         180
        .size:           2
        .value_kind:     hidden_group_size_x
      - .offset:         182
        .size:           2
        .value_kind:     hidden_group_size_y
      - .offset:         184
        .size:           2
        .value_kind:     hidden_group_size_z
      - .offset:         186
        .size:           2
        .value_kind:     hidden_remainder_x
      - .offset:         188
        .size:           2
        .value_kind:     hidden_remainder_y
      - .offset:         190
        .size:           2
        .value_kind:     hidden_remainder_z
      - .offset:         208
        .size:           8
        .value_kind:     hidden_global_offset_x
      - .offset:         216
        .size:           8
        .value_kind:     hidden_global_offset_y
      - .offset:         224
        .size:           8
        .value_kind:     hidden_global_offset_z
      - .offset:         232
        .size:           2
        .value_kind:     hidden_grid_dims
      - .offset:         256
        .size:           8
        .value_kind:     hidden_multigrid_sync_arg
      - .offset:         288
        .size:           4
        .value_kind:     hidden_dynamic_lds_size
    .group_segment_fixed_size: 0
    .kernarg_segment_align: 8
    .kernarg_segment_size: 424
    .language:       OpenCL C
    .language_version:
      - 2
      - 0
    .max_flat_workgroup_size: 512
    .name:           _Z6mk_fwd6Params
    .private_segment_fixed_size: 0
    .sgpr_count:     108
    .sgpr_spill_count: 76
    .symbol:         _Z6mk_fwd6Params.kd
    .uniform_work_group_size: 1
    .uses_dynamic_stack: false
    .vgpr_count:     256
    .vgpr_spill_count: 0
    .wavefront_size: 64
